# GEMM1 tile order: 128 half-width tiles moved to the last round, their zero half skipped (MFMAs + B-fragment LDS reads)
# speedup vs baseline: 1.0265x; 1.0032x over previous
.LBB0_106:
	v_writelane_b32 v246, s52, 32
	s_nop 1
	v_writelane_b32 v246, s53, 33
	v_writelane_b32 v246, s54, 34
	v_writelane_b32 v246, s55, 35
	v_writelane_b32 v246, s56, 36
	v_writelane_b32 v246, s57, 37
	v_writelane_b32 v246, s58, 38
	v_writelane_b32 v246, s59, 39
	v_writelane_b32 v246, s60, 40
	v_writelane_b32 v246, s61, 41
	v_writelane_b32 v246, s62, 42
	v_writelane_b32 v246, s63, 43
	v_writelane_b32 v246, s64, 44
	v_writelane_b32 v246, s65, 45
	v_writelane_b32 v246, s66, 46
	v_writelane_b32 v246, s67, 47
	s_or_b64 exec, exec, s[18:19]
	s_cmpk_lt_i32 s2, 0x880
	s_cselect_b64 s[18:19], -1, 0
	v_readfirstlane_b32 s22, v141
	s_and_b64 vcc, exec, s[18:19]
	s_waitcnt lgkmcnt(0)
	s_barrier
	s_cbranch_vccz .LBB0_108
	s_and_b32 s23, s2, 7
	s_lshr_b32 s24, s2, 3
	s_lshl_b32 s23, s23, 8
	s_add_i32 s23, s23, s24
	s_lshr_b32 s24, s23, 7
	s_lshl_b32 s24, s24, 3
	s_and_b32 s25, s23, 7
	s_add_i32 s38, s24, s25
	s_bfe_u32 s54, s23, 0x40003

.LBB0_114:
	s_add_i32 s67, s67, 1
	s_mul_i32 s27, s67, s22
	s_mul_hi_u32 s28, s67, s90
	s_add_i32 s28, s28, s27
	s_mul_i32 s27, s67, s90
	s_add_u32 s50, s27, s2
	s_addc_u32 s51, s28, s23
	v_cmp_gt_i64_e32 vcc, s[50:51], v[158:159]
	v_cmp_lt_i64_e64 s[36:37], s[50:51], v[156:157]
	s_cbranch_vccnz .LBB0_116
	s_cmpk_lt_u32 s50, 0x800
	s_cbranch_scc1 .Lg1o_full
	s_and_b32 s27, s50, 7
	s_lshl_b32 s27, s27, 4
	s_bfe_u32 s28, s50, 0x40003
	s_add_i32 s48, s27, s28
	s_mov_b32 s46, 16
	s_branch .LBB0_116
.Lg1o_full:
	s_and_b32 s27, s50, 7
	s_lshr_b32 s28, s50, 3
	s_lshl_b32 s27, s27, 8
	s_add_i32 s27, s27, s28
	s_lshr_b32 s28, s27, 7
	s_lshl_b32 s28, s28, 3
	s_and_b32 s29, s27, 7
	s_add_i32 s48, s28, s29
	s_bfe_u32 s46, s27, 0x40003

.LBB0_117:
	ds_read_b128 v[128:131], v177
	ds_read_b128 v[132:135], v177 offset:1024
	ds_read_b128 v[182:185], v177 offset:2048
	ds_read_b128 v[186:189], v177 offset:3072
	s_cmp_eq_u32 s54, 16
	s_cbranch_scc1 .Lg1skipb0
	ds_read_b128 v[190:193], v178
	ds_read_b128 v[194:197], v178 offset:1024
	ds_read_b128 v[198:201], v178 offset:2048
	ds_read_b128 v[202:205], v178 offset:3072
.Lg1skipb0:
	s_add_u32 s28, s56, 0xfffc0080
	s_addc_u32 s29, s57, -1
	s_cmp_eq_u32 vcc_hi, 12
	s_cselect_b32 s61, s27, s29
	s_cselect_b32 s60, s39, s28
	s_cselect_b32 s59, s47, vcc_lo
	s_cselect_b32 s58, s49, s55
	v_lshl_add_u64 v[160:161], s[56:57], 0, v[152:153]
	s_add_i32 m0, s63, 0xc000
	ds_read_b128 v[206:209], v179
	ds_read_b128 v[210:213], v179 offset:1024
	ds_read_b128 v[214:217], v179 offset:2048
	ds_read_b128 v[218:221], v179 offset:3072
	ds_read_b128 v[222:225], v179 offset:4096
	ds_read_b128 v[226:229], v179 offset:5120
	ds_read_b128 v[230:233], v179 offset:6144
	ds_read_b128 v[234:237], v179 offset:7168
	global_load_lds_dwordx4 v[160:161], off
	v_lshl_add_u64 v[160:161], s[56:57], 0, v[154:155]
	s_add_i32 m0, s63, 0xe000
	s_nop 0
	global_load_lds_dwordx4 v[160:161], off
	s_waitcnt vmcnt(8)
	s_waitcnt lgkmcnt(0)
	s_barrier
	s_setprio 1
	s_waitcnt lgkmcnt(0)
	v_mfma_f32_16x16x32_bf16 v[120:123], v[128:131], v[206:209], v[120:123]
	v_mfma_f32_16x16x32_bf16 v[124:127], v[182:185], v[206:209], v[124:127]
	v_mfma_f32_16x16x32_bf16 v[112:115], v[128:131], v[214:217], v[112:115]
	v_mfma_f32_16x16x32_bf16 v[116:119], v[182:185], v[214:217], v[116:119]
	v_mfma_f32_16x16x32_bf16 v[104:107], v[128:131], v[222:225], v[104:107]
	v_mfma_f32_16x16x32_bf16 v[108:111], v[182:185], v[222:225], v[108:111]
	v_mfma_f32_16x16x32_bf16 v[96:99], v[128:131], v[230:233], v[96:99]
	v_mfma_f32_16x16x32_bf16 v[100:103], v[182:185], v[230:233], v[100:103]
	v_mfma_f32_16x16x32_bf16 v[120:123], v[132:135], v[210:213], v[120:123]
	v_mfma_f32_16x16x32_bf16 v[124:127], v[186:189], v[210:213], v[124:127]
	v_mfma_f32_16x16x32_bf16 v[112:115], v[132:135], v[218:221], v[112:115]
	v_mfma_f32_16x16x32_bf16 v[116:119], v[186:189], v[218:221], v[116:119]
	v_mfma_f32_16x16x32_bf16 v[104:107], v[132:135], v[226:229], v[104:107]
	v_mfma_f32_16x16x32_bf16 v[108:111], v[186:189], v[226:229], v[108:111]
	v_mfma_f32_16x16x32_bf16 v[96:99], v[132:135], v[234:237], v[96:99]
	v_mfma_f32_16x16x32_bf16 v[100:103], v[186:189], v[234:237], v[100:103]
	s_setprio 0
	s_cmp_eq_u32 s54, 16
	s_cbranch_scc1 .Lg1skip0
	s_setprio 1
	v_mfma_f32_16x16x32_bf16 v[56:59], v[190:193], v[206:209], v[56:59]
	v_mfma_f32_16x16x32_bf16 v[60:63], v[198:201], v[206:209], v[60:63]
	v_mfma_f32_16x16x32_bf16 v[48:51], v[190:193], v[214:217], v[48:51]
	v_mfma_f32_16x16x32_bf16 v[52:55], v[198:201], v[214:217], v[52:55]
	v_mfma_f32_16x16x32_bf16 v[40:43], v[190:193], v[222:225], v[40:43]
	v_mfma_f32_16x16x32_bf16 v[44:47], v[198:201], v[222:225], v[44:47]
	v_mfma_f32_16x16x32_bf16 v[32:35], v[190:193], v[230:233], v[32:35]
	v_mfma_f32_16x16x32_bf16 v[36:39], v[198:201], v[230:233], v[36:39]
	v_mfma_f32_16x16x32_bf16 v[56:59], v[194:197], v[210:213], v[56:59]
	v_mfma_f32_16x16x32_bf16 v[60:63], v[202:205], v[210:213], v[60:63]
	v_mfma_f32_16x16x32_bf16 v[48:51], v[194:197], v[218:221], v[48:51]
	v_mfma_f32_16x16x32_bf16 v[52:55], v[202:205], v[218:221], v[52:55]
	v_mfma_f32_16x16x32_bf16 v[40:43], v[194:197], v[226:229], v[40:43]
	v_mfma_f32_16x16x32_bf16 v[44:47], v[202:205], v[226:229], v[44:47]
	v_mfma_f32_16x16x32_bf16 v[32:35], v[194:197], v[234:237], v[32:35]
	v_mfma_f32_16x16x32_bf16 v[36:39], v[202:205], v[234:237], v[36:39]
	s_setprio 0
.Lg1skip0:
	s_barrier
	s_add_i32 s28, s24, s62
	v_lshl_add_u64 v[160:161], s[58:59], 0, v[136:137]
	s_mov_b32 m0, s28
	ds_read_b128 v[206:209], v179 offset:16384
	ds_read_b128 v[210:213], v179 offset:17408
	ds_read_b128 v[214:217], v179 offset:18432
	ds_read_b128 v[218:221], v179 offset:19456
	ds_read_b128 v[222:225], v179 offset:20480
	ds_read_b128 v[226:229], v179 offset:21504
	ds_read_b128 v[230:233], v179 offset:22528
	ds_read_b128 v[234:237], v179 offset:23552
	global_load_lds_dwordx4 v[160:161], off
	s_add_i32 m0, s28, 0x2000
	s_add_u32 s28, s58, 0x40000
	v_lshl_add_u64 v[238:239], s[58:59], 0, v[138:139]
	s_addc_u32 s29, s59, 0
	s_add_i32 s30, s25, s62
	global_load_lds_dwordx4 v[238:239], off
	v_lshl_add_u64 v[240:241], s[28:29], 0, v[136:137]
	s_mov_b32 m0, s30
	v_lshl_add_u64 v[242:243], s[60:61], 0, v[148:149]
	global_load_lds_dwordx4 v[240:241], off
	v_lshl_add_u64 v[240:241], s[28:29], 0, v[138:139]
	s_add_i32 m0, s30, 0x2000
	s_nop 0
	global_load_lds_dwordx4 v[240:241], off
	v_lshl_add_u64 v[240:241], s[60:61], 0, v[146:147]
	s_mov_b32 m0, s63
	s_nop 0
	global_load_lds_dwordx4 v[240:241], off
	s_mov_b32 m0, s64
	s_nop 0
	global_load_lds_dwordx4 v[242:243], off
	s_waitcnt vmcnt(8)
	s_waitcnt lgkmcnt(0)
	s_barrier
	s_setprio 1
	s_waitcnt lgkmcnt(0)
	v_mfma_f32_16x16x32_bf16 v[88:91], v[128:131], v[206:209], v[88:91]
	v_mfma_f32_16x16x32_bf16 v[92:95], v[182:185], v[206:209], v[92:95]
	v_mfma_f32_16x16x32_bf16 v[80:83], v[128:131], v[214:217], v[80:83]
	v_mfma_f32_16x16x32_bf16 v[84:87], v[182:185], v[214:217], v[84:87]
	v_mfma_f32_16x16x32_bf16 v[72:75], v[128:131], v[222:225], v[72:75]
	v_mfma_f32_16x16x32_bf16 v[76:79], v[182:185], v[222:225], v[76:79]
	v_mfma_f32_16x16x32_bf16 v[64:67], v[128:131], v[230:233], v[64:67]
	v_mfma_f32_16x16x32_bf16 v[68:71], v[182:185], v[230:233], v[68:71]
	v_mfma_f32_16x16x32_bf16 v[88:91], v[132:135], v[210:213], v[88:91]
	v_mfma_f32_16x16x32_bf16 v[92:95], v[186:189], v[210:213], v[92:95]
	v_mfma_f32_16x16x32_bf16 v[80:83], v[132:135], v[218:221], v[80:83]
	v_mfma_f32_16x16x32_bf16 v[84:87], v[186:189], v[218:221], v[84:87]
	v_mfma_f32_16x16x32_bf16 v[72:75], v[132:135], v[226:229], v[72:75]
	v_mfma_f32_16x16x32_bf16 v[76:79], v[186:189], v[226:229], v[76:79]
	v_mfma_f32_16x16x32_bf16 v[64:67], v[132:135], v[234:237], v[64:67]
	v_mfma_f32_16x16x32_bf16 v[68:71], v[186:189], v[234:237], v[68:71]
	s_setprio 0
	s_cmp_eq_u32 s54, 16
	s_cbranch_scc1 .Lg1skip1
	s_setprio 1
	v_mfma_f32_16x16x32_bf16 v[24:27], v[190:193], v[206:209], v[24:27]
	v_mfma_f32_16x16x32_bf16 v[28:31], v[198:201], v[206:209], v[28:31]
	v_mfma_f32_16x16x32_bf16 v[16:19], v[190:193], v[214:217], v[16:19]
	v_mfma_f32_16x16x32_bf16 v[20:23], v[198:201], v[214:217], v[20:23]
	v_mfma_f32_16x16x32_bf16 v[8:11], v[190:193], v[222:225], v[8:11]
	v_mfma_f32_16x16x32_bf16 v[12:15], v[198:201], v[222:225], v[12:15]
	v_mfma_f32_16x16x32_bf16 v[0:3], v[190:193], v[230:233], v[0:3]
	v_mfma_f32_16x16x32_bf16 v[4:7], v[198:201], v[230:233], v[4:7]
	v_mfma_f32_16x16x32_bf16 v[24:27], v[194:197], v[210:213], v[24:27]
	v_mfma_f32_16x16x32_bf16 v[28:31], v[202:205], v[210:213], v[28:31]
	v_mfma_f32_16x16x32_bf16 v[16:19], v[194:197], v[218:221], v[16:19]
	v_mfma_f32_16x16x32_bf16 v[20:23], v[202:205], v[218:221], v[20:23]
	v_mfma_f32_16x16x32_bf16 v[8:11], v[194:197], v[226:229], v[8:11]
	v_mfma_f32_16x16x32_bf16 v[12:15], v[202:205], v[226:229], v[12:15]
	v_mfma_f32_16x16x32_bf16 v[0:3], v[194:197], v[234:237], v[0:3]
	v_mfma_f32_16x16x32_bf16 v[4:7], v[202:205], v[234:237], v[4:7]
	s_setprio 0
.Lg1skip1:
	s_barrier
	s_add_i32 s30, 0, 0x18000
	v_add_u32_e32 v181, s30, v145
	s_add_i32 s31, 0, 0x1c000
	ds_read_b128 v[128:131], v181
	ds_read_b128 v[132:135], v181 offset:1024
	ds_read_b128 v[182:185], v181 offset:2048
	ds_read_b128 v[186:189], v181 offset:3072
	s_cmp_eq_u32 s54, 16
	s_cbranch_scc1 .Lg1skipb1
	v_add_u32_e32 v181, s31, v145
	ds_read_b128 v[190:193], v181
	ds_read_b128 v[194:197], v181 offset:1024
	ds_read_b128 v[198:201], v181 offset:2048
	ds_read_b128 v[202:205], v181 offset:3072
.Lg1skipb1:
	s_add_u32 s28, s60, 0x40000
	s_addc_u32 s29, s61, 0
	s_mov_b32 m0, s65
	v_lshl_add_u64 v[244:245], s[28:29], 0, v[146:147]
	ds_read_b128 v[206:209], v179 offset:32768
	ds_read_b128 v[210:213], v179 offset:33792
	ds_read_b128 v[214:217], v179 offset:34816
	ds_read_b128 v[218:221], v179 offset:35840
	ds_read_b128 v[222:225], v179 offset:36864
	ds_read_b128 v[226:229], v179 offset:37888
	ds_read_b128 v[230:233], v179 offset:38912
	ds_read_b128 v[234:237], v179 offset:39936
	global_load_lds_dwordx4 v[244:245], off
	v_lshl_add_u64 v[244:245], s[28:29], 0, v[148:149]
	s_mov_b32 m0, s66
	s_nop 0
	global_load_lds_dwordx4 v[244:245], off
	s_waitcnt vmcnt(8)
	s_waitcnt lgkmcnt(0)
	s_barrier
	s_setprio 1
	s_waitcnt lgkmcnt(0)
	v_mfma_f32_16x16x32_bf16 v[120:123], v[128:131], v[206:209], v[120:123]
	v_mfma_f32_16x16x32_bf16 v[124:127], v[182:185], v[206:209], v[124:127]
	v_mfma_f32_16x16x32_bf16 v[112:115], v[128:131], v[214:217], v[112:115]
	v_mfma_f32_16x16x32_bf16 v[116:119], v[182:185], v[214:217], v[116:119]
	v_mfma_f32_16x16x32_bf16 v[104:107], v[128:131], v[222:225], v[104:107]
	v_mfma_f32_16x16x32_bf16 v[108:111], v[182:185], v[222:225], v[108:111]
	v_mfma_f32_16x16x32_bf16 v[96:99], v[128:131], v[230:233], v[96:99]
	v_mfma_f32_16x16x32_bf16 v[100:103], v[182:185], v[230:233], v[100:103]
	v_mfma_f32_16x16x32_bf16 v[120:123], v[132:135], v[210:213], v[120:123]
	v_mfma_f32_16x16x32_bf16 v[124:127], v[186:189], v[210:213], v[124:127]
	v_mfma_f32_16x16x32_bf16 v[112:115], v[132:135], v[218:221], v[112:115]
	v_mfma_f32_16x16x32_bf16 v[116:119], v[186:189], v[218:221], v[116:119]
	v_mfma_f32_16x16x32_bf16 v[104:107], v[132:135], v[226:229], v[104:107]
	v_mfma_f32_16x16x32_bf16 v[108:111], v[186:189], v[226:229], v[108:111]
	v_mfma_f32_16x16x32_bf16 v[96:99], v[132:135], v[234:237], v[96:99]
	v_mfma_f32_16x16x32_bf16 v[100:103], v[186:189], v[234:237], v[100:103]
	s_setprio 0
	s_cmp_eq_u32 s54, 16
	s_cbranch_scc1 .Lg1skip2
	s_setprio 1
	v_mfma_f32_16x16x32_bf16 v[56:59], v[190:193], v[206:209], v[56:59]
	v_mfma_f32_16x16x32_bf16 v[60:63], v[198:201], v[206:209], v[60:63]
	v_mfma_f32_16x16x32_bf16 v[48:51], v[190:193], v[214:217], v[48:51]
	v_mfma_f32_16x16x32_bf16 v[52:55], v[198:201], v[214:217], v[52:55]
	v_mfma_f32_16x16x32_bf16 v[40:43], v[190:193], v[222:225], v[40:43]
	v_mfma_f32_16x16x32_bf16 v[44:47], v[198:201], v[222:225], v[44:47]
	v_mfma_f32_16x16x32_bf16 v[32:35], v[190:193], v[230:233], v[32:35]
	v_mfma_f32_16x16x32_bf16 v[36:39], v[198:201], v[230:233], v[36:39]
	v_mfma_f32_16x16x32_bf16 v[56:59], v[194:197], v[210:213], v[56:59]
	v_mfma_f32_16x16x32_bf16 v[60:63], v[202:205], v[210:213], v[60:63]
	v_mfma_f32_16x16x32_bf16 v[48:51], v[194:197], v[218:221], v[48:51]
	v_mfma_f32_16x16x32_bf16 v[52:55], v[202:205], v[218:221], v[52:55]
	v_mfma_f32_16x16x32_bf16 v[40:43], v[194:197], v[226:229], v[40:43]
	v_mfma_f32_16x16x32_bf16 v[44:47], v[202:205], v[226:229], v[44:47]
	v_mfma_f32_16x16x32_bf16 v[32:35], v[194:197], v[234:237], v[32:35]
	v_mfma_f32_16x16x32_bf16 v[36:39], v[202:205], v[234:237], v[36:39]
	s_setprio 0
.Lg1skip2:
	s_barrier
	s_add_i32 s28, s30, s62
	v_lshl_add_u64 v[160:161], v[160:161], 0, s[40:41]
	s_mov_b32 m0, s28
	ds_read_b128 v[206:209], v179 offset:49152
	ds_read_b128 v[210:213], v179 offset:50176
	ds_read_b128 v[214:217], v179 offset:51200
	ds_read_b128 v[218:221], v179 offset:52224
	ds_read_b128 v[222:225], v179 offset:53248
	ds_read_b128 v[226:229], v179 offset:54272
	ds_read_b128 v[230:233], v179 offset:55296
	ds_read_b128 v[234:237], v179 offset:56320
	global_load_lds_dwordx4 v[160:161], off
	s_add_i32 m0, s28, 0x2000
	s_add_u32 s28, s58, 0x40080
	v_lshl_add_u64 v[160:161], v[238:239], 0, s[40:41]
	s_addc_u32 s29, s59, 0
	s_add_i32 s30, s31, s62
	global_load_lds_dwordx4 v[160:161], off
	v_lshl_add_u64 v[160:161], s[28:29], 0, v[136:137]
	s_mov_b32 m0, s30
	s_nop 0
	global_load_lds_dwordx4 v[160:161], off
	v_lshl_add_u64 v[160:161], s[28:29], 0, v[138:139]
	s_add_i32 m0, s30, 0x2000
	s_nop 0
	global_load_lds_dwordx4 v[160:161], off
	v_lshl_add_u64 v[160:161], v[240:241], 0, s[40:41]
	s_mov_b32 m0, s71
	s_nop 0
	global_load_lds_dwordx4 v[160:161], off
	v_lshl_add_u64 v[160:161], v[242:243], 0, s[40:41]
	s_mov_b32 m0, s91
	s_nop 0
	global_load_lds_dwordx4 v[160:161], off
	s_waitcnt vmcnt(8)
	s_waitcnt lgkmcnt(0)
	s_barrier
	s_setprio 1
	s_waitcnt lgkmcnt(0)
	v_mfma_f32_16x16x32_bf16 v[88:91], v[128:131], v[206:209], v[88:91]
	v_mfma_f32_16x16x32_bf16 v[92:95], v[182:185], v[206:209], v[92:95]
	v_mfma_f32_16x16x32_bf16 v[80:83], v[128:131], v[214:217], v[80:83]
	v_mfma_f32_16x16x32_bf16 v[84:87], v[182:185], v[214:217], v[84:87]
	v_mfma_f32_16x16x32_bf16 v[72:75], v[128:131], v[222:225], v[72:75]
	v_mfma_f32_16x16x32_bf16 v[76:79], v[182:185], v[222:225], v[76:79]
	v_mfma_f32_16x16x32_bf16 v[64:67], v[128:131], v[230:233], v[64:67]
	v_mfma_f32_16x16x32_bf16 v[68:71], v[182:185], v[230:233], v[68:71]
	v_mfma_f32_16x16x32_bf16 v[88:91], v[132:135], v[210:213], v[88:91]
	v_mfma_f32_16x16x32_bf16 v[92:95], v[186:189], v[210:213], v[92:95]
	v_mfma_f32_16x16x32_bf16 v[80:83], v[132:135], v[218:221], v[80:83]
	v_mfma_f32_16x16x32_bf16 v[84:87], v[186:189], v[218:221], v[84:87]
	v_mfma_f32_16x16x32_bf16 v[72:75], v[132:135], v[226:229], v[72:75]
	v_mfma_f32_16x16x32_bf16 v[76:79], v[186:189], v[226:229], v[76:79]
	v_mfma_f32_16x16x32_bf16 v[64:67], v[132:135], v[234:237], v[64:67]
	v_mfma_f32_16x16x32_bf16 v[68:71], v[186:189], v[234:237], v[68:71]
	s_setprio 0
	s_cmp_eq_u32 s54, 16
	s_cbranch_scc1 .Lg1skip3
	s_setprio 1
	v_mfma_f32_16x16x32_bf16 v[24:27], v[190:193], v[206:209], v[24:27]
	v_mfma_f32_16x16x32_bf16 v[28:31], v[198:201], v[206:209], v[28:31]
	v_mfma_f32_16x16x32_bf16 v[16:19], v[190:193], v[214:217], v[16:19]
	v_mfma_f32_16x16x32_bf16 v[20:23], v[198:201], v[214:217], v[20:23]
	v_mfma_f32_16x16x32_bf16 v[8:11], v[190:193], v[222:225], v[8:11]
	v_mfma_f32_16x16x32_bf16 v[12:15], v[198:201], v[222:225], v[12:15]
	v_mfma_f32_16x16x32_bf16 v[0:3], v[190:193], v[230:233], v[0:3]
	v_mfma_f32_16x16x32_bf16 v[4:7], v[198:201], v[230:233], v[4:7]
	v_mfma_f32_16x16x32_bf16 v[24:27], v[194:197], v[210:213], v[24:27]
	v_mfma_f32_16x16x32_bf16 v[28:31], v[202:205], v[210:213], v[28:31]
	v_mfma_f32_16x16x32_bf16 v[16:19], v[194:197], v[218:221], v[16:19]
	v_mfma_f32_16x16x32_bf16 v[20:23], v[202:205], v[218:221], v[20:23]
	v_mfma_f32_16x16x32_bf16 v[8:11], v[194:197], v[226:229], v[8:11]
	v_mfma_f32_16x16x32_bf16 v[12:15], v[202:205], v[226:229], v[12:15]
	v_mfma_f32_16x16x32_bf16 v[0:3], v[194:197], v[234:237], v[0:3]
	v_mfma_f32_16x16x32_bf16 v[4:7], v[202:205], v[234:237], v[4:7]
	s_setprio 0
.Lg1skip3:
	s_barrier
	s_add_i32 vcc_hi, vcc_hi, 2
	s_add_u32 s56, s56, 0x100
	s_addc_u32 s57, s57, 0
	s_add_u32 s55, s55, 0x100
	s_addc_u32 vcc_lo, vcc_lo, 0
	s_cmp_gt_u32 vcc_hi, 13
	s_cbranch_scc0 .LBB0_117
	s_and_b64 vcc, exec, s[42:43]
	s_cbranch_vccz .LBB0_120
	s_barrier
